# trim stack + P7 zero-fill only for out-of-bounds lanes in the 7 regular row-load blocks (56 fewer v_mov per iteration)
# speedup vs baseline: 1.0074x; 1.0042x over previous
; __device__ __forceinline__ void ffnconv_phase(const bf16* h, bf16* gout, const float* cw, const float* cb, int T, int vcu, int NT) {
;     ...
;         for (int t = t0; t < t1; t += RS) {
;             v4u gn_[RS], vn_[RS];
; #pragma unroll
;             for (int q = 0; q < RS; ++q) { gn_[q] = z4; vn_[q] = z4; if (t + q + 1 < MC) { gn_[q] = __builtin_nontemporal_load((const v4u*)(p + (size_t)(q + 1) * NUP)); vn_[q] = __builtin_nontemporal_load((const v4u*)(p + (size_t)(q + 1) * NUP + DFF)); } }
.LBB0_882:
	v_add_u32_e32 v1, -7, v211
	v_cmp_gt_i32_e32 vcc, s68, v1
	s_mov_b64 s[24:25], exec
	s_andn2_b64 exec, exec, vcc
	s_cbranch_execz .Lp7nz_1
	v_mov_b32_e32 v108, 0
	v_mov_b32_e32 v109, 0
	v_mov_b32_e32 v110, 0
	v_mov_b32_e32 v111, 0
	v_mov_b32_e32 v112, 0
	v_mov_b32_e32 v113, 0
	v_mov_b32_e32 v114, 0
	v_mov_b32_e32 v115, 0
.Lp7nz_1:
	s_and_b64 exec, s[24:25], vcc
	s_cbranch_execz .LBB0_884
	v_lshl_add_u64 v[2:3], v[152:153], 0, v[116:117]
	v_lshl_add_u64 v[36:37], v[154:155], 0, v[116:117]
	global_load_dwordx4 v[108:111], v[2:3], off nt
	global_load_dwordx4 v[112:115], v[36:37], off nt
.LBB0_884:
	s_or_b64 exec, exec, s[24:25]
	v_add_u32_e32 v1, 1, v1
	v_cmp_gt_i32_e32 vcc, s68, v1
	s_mov_b64 s[24:25], exec
	s_andn2_b64 exec, exec, vcc
	s_cbranch_execz .Lp7nz_2
	v_mov_b32_e32 v84, 0
	v_mov_b32_e32 v85, 0
	v_mov_b32_e32 v86, 0
	v_mov_b32_e32 v87, 0
	v_mov_b32_e32 v104, 0
	v_mov_b32_e32 v105, 0
	v_mov_b32_e32 v106, 0
	v_mov_b32_e32 v107, 0
.Lp7nz_2:
	s_and_b64 exec, s[24:25], vcc
	s_cbranch_execz .LBB0_886
	v_lshl_add_u64 v[2:3], v[156:157], 0, v[116:117]
	v_lshl_add_u64 v[36:37], v[158:159], 0, v[116:117]
	global_load_dwordx4 v[84:87], v[2:3], off nt
	global_load_dwordx4 v[104:107], v[36:37], off nt
.LBB0_886:
	s_or_b64 exec, exec, s[24:25]
	v_add_u32_e32 v1, 1, v1
	v_cmp_gt_i32_e32 vcc, s68, v1
	s_mov_b64 s[24:25], exec
	s_andn2_b64 exec, exec, vcc
	s_cbranch_execz .Lp7nz_3
	v_mov_b32_e32 v76, 0
	v_mov_b32_e32 v77, 0
	v_mov_b32_e32 v78, 0
	v_mov_b32_e32 v79, 0
	v_mov_b32_e32 v80, 0
	v_mov_b32_e32 v81, 0
	v_mov_b32_e32 v82, 0
	v_mov_b32_e32 v83, 0
.Lp7nz_3:
	s_and_b64 exec, s[24:25], vcc
	s_cbranch_execz .LBB0_888
	v_lshl_add_u64 v[2:3], v[160:161], 0, v[116:117]
	v_lshl_add_u64 v[36:37], v[162:163], 0, v[116:117]
	global_load_dwordx4 v[76:79], v[2:3], off nt
	global_load_dwordx4 v[80:83], v[36:37], off nt
.LBB0_888:
	s_or_b64 exec, exec, s[24:25]
	v_add_u32_e32 v1, 1, v1
	v_cmp_gt_i32_e32 vcc, s68, v1
	s_mov_b64 s[24:25], exec
	s_andn2_b64 exec, exec, vcc
	s_cbranch_execz .Lp7nz_4
	v_mov_b32_e32 v68, 0
	v_mov_b32_e32 v69, 0
	v_mov_b32_e32 v70, 0
	v_mov_b32_e32 v71, 0
	v_mov_b32_e32 v72, 0
	v_mov_b32_e32 v73, 0
	v_mov_b32_e32 v74, 0
	v_mov_b32_e32 v75, 0
.Lp7nz_4:
	s_and_b64 exec, s[24:25], vcc
	s_cbranch_execz .LBB0_890
	v_lshl_add_u64 v[2:3], v[164:165], 0, v[116:117]
	v_lshl_add_u64 v[36:37], v[166:167], 0, v[116:117]
	global_load_dwordx4 v[68:71], v[2:3], off nt
	global_load_dwordx4 v[72:75], v[36:37], off nt
.LBB0_890:
	s_or_b64 exec, exec, s[24:25]
	v_add_u32_e32 v1, 1, v1
	v_cmp_gt_i32_e32 vcc, s68, v1
	s_mov_b64 s[24:25], exec
	s_andn2_b64 exec, exec, vcc
	s_cbranch_execz .Lp7nz_5
	v_mov_b32_e32 v60, 0
	v_mov_b32_e32 v61, 0
	v_mov_b32_e32 v62, 0
	v_mov_b32_e32 v63, 0
	v_mov_b32_e32 v64, 0
	v_mov_b32_e32 v65, 0
	v_mov_b32_e32 v66, 0
	v_mov_b32_e32 v67, 0
.Lp7nz_5:
	s_and_b64 exec, s[24:25], vcc
	s_cbranch_execz .LBB0_892
	v_lshl_add_u64 v[2:3], v[168:169], 0, v[116:117]
	v_lshl_add_u64 v[36:37], v[170:171], 0, v[116:117]
	global_load_dwordx4 v[60:63], v[2:3], off nt
	global_load_dwordx4 v[64:67], v[36:37], off nt
.LBB0_892:
	s_or_b64 exec, exec, s[24:25]
	v_add_u32_e32 v1, 1, v1
	v_cmp_gt_i32_e32 vcc, s68, v1
	s_mov_b64 s[24:25], exec
	s_andn2_b64 exec, exec, vcc
	s_cbranch_execz .Lp7nz_6
	v_mov_b32_e32 v52, 0
	v_mov_b32_e32 v53, 0
	v_mov_b32_e32 v54, 0
	v_mov_b32_e32 v55, 0
	v_mov_b32_e32 v56, 0
	v_mov_b32_e32 v57, 0
	v_mov_b32_e32 v58, 0
	v_mov_b32_e32 v59, 0
.Lp7nz_6:
	s_and_b64 exec, s[24:25], vcc
	s_cbranch_execz .LBB0_894
	v_lshl_add_u64 v[2:3], v[172:173], 0, v[116:117]
	v_lshl_add_u64 v[36:37], v[174:175], 0, v[116:117]
	global_load_dwordx4 v[52:55], v[2:3], off nt
	global_load_dwordx4 v[56:59], v[36:37], off nt
.LBB0_894:
	s_or_b64 exec, exec, s[24:25]
	v_add_u32_e32 v1, 1, v1
	v_cmp_gt_i32_e32 vcc, s68, v1
	s_mov_b64 s[24:25], exec
	s_andn2_b64 exec, exec, vcc
	s_cbranch_execz .Lp7nz_7
	v_mov_b32_e32 v36, 0
	v_mov_b32_e32 v37, 0
	v_mov_b32_e32 v38, 0
	v_mov_b32_e32 v39, 0
	v_mov_b32_e32 v40, 0
	v_mov_b32_e32 v41, 0
	v_mov_b32_e32 v42, 0
	v_mov_b32_e32 v43, 0
.Lp7nz_7:
	s_and_b64 exec, s[24:25], vcc
	s_cbranch_execz .LBB0_896
	v_lshl_add_u64 v[2:3], v[176:177], 0, v[116:117]
	v_lshl_add_u64 v[40:41], v[178:179], 0, v[116:117]
	global_load_dwordx4 v[36:39], v[2:3], off nt
	s_nop 0
	global_load_dwordx4 v[40:43], v[40:41], off nt
